# attention: one static s_setprio 1 for the older half (waves 0-3) before each flash unit's tile loop, reset at the unit epilogue
# speedup vs baseline: 1.0110x; 1.0110x over previous
; __device__ __forceinline__ float bflo(unsigned w) { return __uint_as_float(w << 16); }
; __device__ __forceinline__ float bfhi(unsigned w) { return __uint_as_float(w & 0xffff0000u); }
; __device__ __forceinline__ unsigned pk2(float lo, float hi) { const f32x2 v = {lo, hi}; return __builtin_bit_cast(unsigned, __builtin_convertvector(v, bf16x2_t)); }
; __device__ __forceinline__ float ex2f(float x) { return __builtin_amdgcn_exp2f(x); }
; template <int DQK, int DV, int MODE>
; __device__ __forceinline__ void flash_unit(LAS unsigned char* lds, const bf16* Qp, int qpitch, const bf16* K0, int kpitch, const bf16* K1, const bf16* VT, int vpitch,
;                                            bf16* Op, int opitch, int NT, int jbase, int qpos0) {
;     ...
;         const float pos = (float)(qpos0 + wid * 32 + r32);
;         const u32x4 xa = __builtin_bit_cast(u32x4, qf[ND0 - 2]), xb = __builtin_bit_cast(u32x4, qf[ND0 - 1]); u32x4 ra, rb;
; #pragma unroll
;         for (int e = 0; e < 4; ++e) { const float a0 = bflo(xa[e]), a1 = bfhi(xa[e]), b0 = bflo(xb[e]), b1 = bfhi(xb[e]);
;             float s0_, c0_, s1_, c1_; sincos_rev(pos * ex2f(-(float)(8 * hi + 2 * e) * (2.0f / 32.0f) * LG2_10000), s0_, c0_); sincos_rev(pos * ex2f(-(float)(8 * hi + 2 * e + 1) * (2.0f / 32.0f) * LG2_10000), s1_, c1_);
;             ra[e] = pk2(a0 * c0_ - b0 * s0_, a1 * c1_ - b1 * s1_); rb[e] = pk2(b0 * c0_ + a0 * s0_, b1 * c1_ + a1 * s1_); }
;         qf[ND0 - 2] = __builtin_bit_cast(bf16x8, ra); qf[ND0 - 1] = __builtin_bit_cast(bf16x8, rb);
.LBB0_540:
	s_or_b64 exec, exec, s[26:27]
	global_load_dwordx4 v[64:67], v[156:157], off offset:128
	v_or_b32_e32 v10, s8, v17
	v_add_u32_e32 v10, s66, v10
	v_cvt_f32_i32_e32 v20, v10
	v_cvt_f32_ubyte0_e32 v10, v154
	v_mul_f32_e32 v10, 0xbd800000, v10
	v_mul_f32_e32 v10, 0x41549a78, v10
	v_exp_f32_e32 v10, v10
	v_or_b32_e32 v11, 1, v154
	v_cvt_f32_ubyte0_e32 v11, v11
	v_mad_u32_u24 v0, v17, s51, v154
	v_mul_f32_e32 v11, 0xbd800000, v11
	v_lshl_add_u32 v169, v0, 1, 0
	v_mul_u32_u24_e32 v0, 0x88, v17
	v_mul_f32_e32 v11, 0x41549a78, v11
	v_add3_u32 v165, 0, v154, v0
	v_mul_f32_e32 v0, v10, v20
	v_exp_f32_e32 v11, v11
	v_mul_f32_e32 v10, 0.15915494, v0
	v_floor_f32_e32 v10, v10
	v_fma_f32 v0, v0, 0.15915494, -v10
	v_sin_f32_e32 v10, v0
	v_cos_f32_e32 v12, v0
	v_mul_f32_e32 v0, v11, v20
	v_mul_f32_e32 v11, 0.15915494, v0
	v_floor_f32_e32 v11, v11
	v_fma_f32 v0, v0, 0.15915494, -v11
	v_sin_f32_e32 v11, v0
	v_cos_f32_e32 v13, v0
	v_or_b32_e32 v0, 2, v154
	v_cvt_f32_ubyte0_e32 v0, v0
	v_mul_f32_e32 v0, 0xbd800000, v0
	v_mul_f32_e32 v0, 0x41549a78, v0
	v_lshlrev_b32_e32 v14, 16, v6
	v_and_b32_e32 v15, 0xffff0000, v6
	v_exp_f32_e32 v0, v0
	v_or_b32_e32 v6, 3, v154
	v_cvt_f32_ubyte0_e32 v6, v6
	v_mul_f32_e32 v6, 0xbd800000, v6
	v_mul_f32_e32 v6, 0x41549a78, v6
	v_mul_f32_e32 v0, v0, v20
	v_exp_f32_e32 v6, v6
	v_lshlrev_b32_e32 v16, 16, v2
	v_and_b32_e32 v17, 0xffff0000, v2
	v_mul_f32_e32 v2, 0.15915494, v0
	v_pk_mul_f32 v[18:19], v[10:11], v[16:17]
	v_pk_mul_f32 v[10:11], v[10:11], v[14:15]
	v_floor_f32_e32 v2, v2
	v_pk_fma_f32 v[10:11], v[12:13], v[16:17], v[10:11]
	v_fma_f32 v0, v0, 0.15915494, -v2
	v_pk_fma_f32 v[18:19], v[12:13], v[14:15], v[18:19] neg_lo:[0,0,1] neg_hi:[0,0,1]
	v_cvt_pk_bf16_f32 v124, v10, v11
	v_sin_f32_e32 v10, v0
	v_cos_f32_e32 v12, v0
	v_mul_f32_e32 v0, v6, v20
	v_mul_f32_e32 v2, 0.15915494, v0
	v_floor_f32_e32 v2, v2
	v_fma_f32 v0, v0, 0.15915494, -v2
	v_sin_f32_e32 v11, v0
	v_cos_f32_e32 v13, v0
	v_lshlrev_b32_e32 v2, 16, v3
	v_and_b32_e32 v3, 0xffff0000, v3
	v_or_b32_e32 v0, 4, v154
	v_lshlrev_b32_e32 v6, 16, v7
	v_and_b32_e32 v7, 0xffff0000, v7
	v_pk_mul_f32 v[14:15], v[10:11], v[2:3]
	v_cvt_f32_ubyte0_e32 v0, v0
	v_pk_fma_f32 v[14:15], v[12:13], v[6:7], v[14:15] neg_lo:[0,0,1] neg_hi:[0,0,1]
	v_mul_f32_e32 v0, 0xbd800000, v0
	v_pk_mul_f32 v[6:7], v[10:11], v[6:7]
	v_mul_f32_e32 v0, 0x41549a78, v0
	v_pk_fma_f32 v[2:3], v[12:13], v[2:3], v[6:7]
	v_exp_f32_e32 v0, v0
	v_cvt_pk_bf16_f32 v125, v2, v3
	v_or_b32_e32 v3, 5, v154
	v_cvt_f32_ubyte0_e32 v3, v3
	v_mul_f32_e32 v3, 0xbd800000, v3
	v_mul_f32_e32 v3, 0x41549a78, v3
	v_mul_f32_e32 v0, v0, v20
	v_exp_f32_e32 v3, v3
	v_mul_f32_e32 v2, 0.15915494, v0
	v_floor_f32_e32 v2, v2
	v_fma_f32 v0, v0, 0.15915494, -v2
	v_sin_f32_e32 v2, v0
	v_cos_f32_e32 v6, v0
	v_mul_f32_e32 v0, v3, v20
	v_mul_f32_e32 v3, 0.15915494, v0
	v_floor_f32_e32 v3, v3
	v_fma_f32 v0, v0, 0.15915494, -v3
	v_sin_f32_e32 v3, v0
	v_cos_f32_e32 v7, v0
	v_or_b32_e32 v0, 6, v154
	v_lshlrev_b32_e32 v10, 16, v8
	v_and_b32_e32 v11, 0xffff0000, v8
	v_lshlrev_b32_e32 v12, 16, v4
	v_and_b32_e32 v13, 0xffff0000, v4
	v_cvt_f32_ubyte0_e32 v0, v0
	v_cvt_pk_bf16_f32 v121, v14, v15
	v_pk_mul_f32 v[14:15], v[2:3], v[12:13]
	v_mul_f32_e32 v0, 0xbd800000, v0
	v_pk_mul_f32 v[2:3], v[2:3], v[10:11]
	v_mul_f32_e32 v0, 0x41549a78, v0
	v_pk_fma_f32 v[2:3], v[6:7], v[12:13], v[2:3]
	v_exp_f32_e32 v0, v0
	v_cvt_pk_bf16_f32 v126, v2, v3
	v_or_b32_e32 v3, 7, v154
	v_cvt_f32_ubyte0_e32 v3, v3
	v_mul_f32_e32 v3, 0xbd800000, v3
	v_mul_f32_e32 v3, 0x41549a78, v3
	v_mul_f32_e32 v0, v0, v20
	v_exp_f32_e32 v3, v3
	v_mul_f32_e32 v2, 0.15915494, v0
	v_floor_f32_e32 v2, v2
	v_fma_f32 v0, v0, 0.15915494, -v2
	v_pk_fma_f32 v[14:15], v[6:7], v[10:11], v[14:15] neg_lo:[0,0,1] neg_hi:[0,0,1]
	v_sin_f32_e32 v2, v0
	v_cos_f32_e32 v6, v0
	v_mul_f32_e32 v0, v3, v20
	v_mul_f32_e32 v3, 0.15915494, v0
	v_floor_f32_e32 v3, v3
	v_fma_f32 v0, v0, 0.15915494, -v3
	v_sin_f32_e32 v3, v0
	v_cos_f32_e32 v7, v0
	v_lshlrev_b32_e32 v8, 16, v9
	v_and_b32_e32 v9, 0xffff0000, v9
	v_lshlrev_b32_e32 v4, 16, v5
	v_and_b32_e32 v5, 0xffff0000, v5
	s_lshl_b32 s27, s64, 2
	s_ashr_i32 s26, s65, 7
	v_pk_mul_f32 v[10:11], v[2:3], v[4:5]
	v_pk_mul_f32 v[2:3], v[2:3], v[8:9]
	s_add_i32 s26, s26, s27
	v_pk_fma_f32 v[10:11], v[6:7], v[8:9], v[10:11] neg_lo:[0,0,1] neg_hi:[0,0,1]
	v_pk_fma_f32 v[2:3], v[6:7], v[4:5], v[2:3]
	v_cvt_pk_bf16_f32 v120, v18, v19
	v_cvt_pk_bf16_f32 v122, v14, v15
	v_cvt_pk_bf16_f32 v123, v10, v11
	s_cmp_ge_u32 s65, 0x100
	s_cbranch_scc1 .Lprio_skip
	s_setprio 1
